# grid barrier: XCD leader releases its XCD (XGEN add) before its own acquire invalidate instead of after
# baseline (speedup 1.0000x reference)
; __device__ __forceinline__ unsigned xb_ld(unsigned* q)              { return __hip_atomic_load(q, __ATOMIC_RELAXED, __HIP_MEMORY_SCOPE_AGENT); }
; __device__ __forceinline__ unsigned xb_add(unsigned* q, unsigned v) { return __hip_atomic_fetch_add(q, v, __ATOMIC_RELAXED, __HIP_MEMORY_SCOPE_AGENT); }
; #define XB_SPIN(cond, bar) do { unsigned _sp = 0; while (cond) { __builtin_amdgcn_s_sleep(1); \
;     if ((++_sp & 255u) == 0u) { if (xb_ld(&(bar)[XB_TMO])) break; if (_sp > XB_SPIN_CAP) { atomicAdd(&(bar)[XB_TMO], 1u); break; } } } } while (0)
; __device__ __forceinline__ void xcd_barrier(const XcdBarrier& b) {
;     ...
;             const unsigned og = xb_add(&bar[XB_TOP], 1u);
;             const unsigned tg = og / nx;
;             if (og + 1u == (tg + 1u) * nx) xb_add(&bar[XB_TOPGEN], 1u);
;             else XB_SPIN(xb_ld(&bar[XB_TOPGEN]) == tg, bar);
;             __builtin_amdgcn_fence(__ATOMIC_ACQUIRE, "agent");
;             xb_add(&bar[XB_XGEN(b.x)], 1u);
;             asm volatile("s_waitcnt vmcnt(0)" ::: "memory");
.LBB0_21:
	s_or_b64 exec, exec, s[12:13]
	v_readlane_b32 s12, v254, 59
	v_readlane_b32 s13, v254, 60
	s_waitcnt vmcnt(0)
	s_nop 4
	global_atomic_add v1, v203, s[12:13]
	buffer_inv sc1
	s_waitcnt vmcnt(0)
